# the last down-projection's epilogue also produces the final normalised output (final phase and its barrier removed, last residual write skipped)
# speedup vs baseline: 1.0257x; 1.0027x over previous
.LBB0_10:
	s_mov_b64 s[2:3], -1
	s_mov_b64 s[12:13], 0
	s_cmp_lt_i32 s10, 37
	s_mov_b64 s[0:1], 0
	s_cbranch_scc1 .LBB0_21
	s_cmp_eq_u32 s10, 37
	s_mov_b64 s[0:1], -1
	s_cbranch_scc0 .LBB0_76
	v_mov_b32_e32 v0, v202
	v_readlane_b32 s0, v252, 4
	v_ashrrev_i32_e32 v2, 6, v0
	s_nop 0
	v_add_u32_e32 v18, s0, v2
	v_cmp_gt_i32_e32 vcc, s37, v18
	v_readlane_b32 s1, v252, 2
	s_cmp_eq_u32 s1, 0x100
	s_cbranch_scc0 .Lfin_keep
	s_mov_b64 vcc, 0
.Lfin_keep:
	s_and_saveexec_b64 s[14:15], vcc
	s_cbranch_execz .LBB0_75
	v_lshlrev_b32_e32 v0, 4, v0
	v_and_b32_e32 v0, 0x3f0, v0
	global_load_dwordx4 v[2:5], v0, s[4:5]
	global_load_dwordx4 v[6:9], v0, s[4:5] offset:1024
	global_load_dwordx4 v[10:13], v0, s[4:5] offset:2048
	global_load_dwordx4 v[14:17], v0, s[4:5] offset:3072
	v_readlane_b32 s0, v252, 5
	v_readlane_b32 s1, v252, 6
	v_lshl_add_u64 v[84:85], s[6:7], 0, v[0:1]
	s_mov_b64 s[16:17], 0
	v_lshl_add_u64 v[82:83], s[0:1], 0, v[0:1]
	s_branch .LBB0_15

.LBB0_182:
	s_add_i32 s91, s2, 2
	s_add_u32 s12, s34, 0x80
	s_addc_u32 s3, s35, 0
	s_add_i32 s13, 0, 0x10000
	v_add_u32_e32 v142, s13, v183
	ds_read_b128 v[130:133], v142
	ds_read_b128 v[134:137], v142 offset:1024
	ds_read_b128 v[138:141], v142 offset:2048
	ds_read_b128 v[142:145], v142 offset:3072
	s_cmp_eq_u32 s88, s2
	s_cselect_b32 s2, s0, s12
	s_cselect_b32 s3, s1, s3
	s_cselect_b32 s43, s41, s90
	s_cselect_b32 s42, s40, s89
	v_lshl_add_u64 v[190:191], s[34:35], 0, v[174:175]
	s_add_i32 m0, s55, 0xc000
	ds_read_b128 v[146:149], v184
	ds_read_b128 v[150:153], v184 offset:1024
	ds_read_b128 v[154:157], v184 offset:2048
	ds_read_b128 v[158:161], v184 offset:3072
	ds_read_b128 v[162:165], v184 offset:4096
	ds_read_b128 v[166:169], v184 offset:5120
	ds_read_b128 v[178:181], v184 offset:6144
	ds_read_b128 v[186:189], v184 offset:7168
	global_load_lds_dwordx4 v[190:191], off
	v_lshl_add_u64 v[190:191], s[34:35], 0, v[176:177]
	s_add_i32 m0, s55, 0xe000
	s_nop 0
	global_load_lds_dwordx4 v[190:191], off
	s_waitcnt lgkmcnt(8)
	s_barrier
	s_waitcnt lgkmcnt(0)
	s_waitcnt lgkmcnt(0)
	v_mfma_f32_16x16x32_bf16 v[126:129], v[130:133], v[146:149], v[126:129]
	v_mfma_f32_16x16x32_bf16 v[122:125], v[138:141], v[146:149], v[122:125]
	v_mfma_f32_16x16x32_bf16 v[118:121], v[130:133], v[154:157], v[118:121]
	v_mfma_f32_16x16x32_bf16 v[114:117], v[138:141], v[154:157], v[114:117]
	v_mfma_f32_16x16x32_bf16 v[110:113], v[130:133], v[162:165], v[110:113]
	v_mfma_f32_16x16x32_bf16 v[106:109], v[138:141], v[162:165], v[106:109]
	v_mfma_f32_16x16x32_bf16 v[102:105], v[130:133], v[178:181], v[102:105]
	v_mfma_f32_16x16x32_bf16 v[98:101], v[138:141], v[178:181], v[98:101]
	v_mfma_f32_16x16x32_bf16 v[126:129], v[134:137], v[150:153], v[126:129]
	v_mfma_f32_16x16x32_bf16 v[122:125], v[142:145], v[150:153], v[122:125]
	v_mfma_f32_16x16x32_bf16 v[118:121], v[134:137], v[158:161], v[118:121]
	v_mfma_f32_16x16x32_bf16 v[114:117], v[142:145], v[158:161], v[114:117]
	v_mfma_f32_16x16x32_bf16 v[110:113], v[134:137], v[166:169], v[110:113]
	v_mfma_f32_16x16x32_bf16 v[106:109], v[142:145], v[166:169], v[106:109]
	v_mfma_f32_16x16x32_bf16 v[102:105], v[134:137], v[186:189], v[102:105]
	v_mfma_f32_16x16x32_bf16 v[98:101], v[142:145], v[186:189], v[98:101]
	s_barrier
	s_add_i32 s92, 0, 0x14000
	s_add_i32 s12, s13, s54
	v_add_u32_e32 v185, s92, v183
	v_lshl_add_u64 v[230:231], s[42:43], 0, v[170:171]
	s_mov_b32 m0, s12
	ds_read_b128 v[190:193], v185
	ds_read_b128 v[194:197], v185 offset:1024
	ds_read_b128 v[198:201], v185 offset:2048
	ds_read_b128 v[226:229], v185 offset:3072
	global_load_lds_dwordx4 v[230:231], off
	v_lshl_add_u64 v[232:233], s[42:43], 0, v[172:173]
	s_add_i32 m0, s12, 0x2000
	s_nop 0
	global_load_lds_dwordx4 v[232:233], off
	s_barrier
	s_waitcnt lgkmcnt(0)
	s_waitcnt lgkmcnt(0)
	v_mfma_f32_16x16x32_bf16 v[62:65], v[190:193], v[146:149], v[62:65]
	v_mfma_f32_16x16x32_bf16 v[58:61], v[198:201], v[146:149], v[58:61]
	v_mfma_f32_16x16x32_bf16 v[54:57], v[190:193], v[154:157], v[54:57]
	v_mfma_f32_16x16x32_bf16 v[50:53], v[198:201], v[154:157], v[50:53]
	v_mfma_f32_16x16x32_bf16 v[46:49], v[190:193], v[162:165], v[46:49]
	v_mfma_f32_16x16x32_bf16 v[42:45], v[198:201], v[162:165], v[42:45]
	v_mfma_f32_16x16x32_bf16 v[38:41], v[190:193], v[178:181], v[38:41]
	v_mfma_f32_16x16x32_bf16 v[34:37], v[198:201], v[178:181], v[34:37]
	v_mfma_f32_16x16x32_bf16 v[62:65], v[194:197], v[150:153], v[62:65]
	v_mfma_f32_16x16x32_bf16 v[58:61], v[226:229], v[150:153], v[58:61]
	v_mfma_f32_16x16x32_bf16 v[54:57], v[194:197], v[158:161], v[54:57]
	v_mfma_f32_16x16x32_bf16 v[50:53], v[226:229], v[158:161], v[50:53]
	v_mfma_f32_16x16x32_bf16 v[46:49], v[194:197], v[166:169], v[46:49]
	v_mfma_f32_16x16x32_bf16 v[42:45], v[226:229], v[166:169], v[42:45]
	v_mfma_f32_16x16x32_bf16 v[38:41], v[194:197], v[186:189], v[38:41]
	v_mfma_f32_16x16x32_bf16 v[34:37], v[226:229], v[186:189], v[34:37]
	s_mov_b32 m0, s55
	v_lshl_add_u64 v[234:235], s[2:3], 0, v[170:171]
	s_barrier
	ds_read_b128 v[146:149], v184 offset:16384
	ds_read_b128 v[150:153], v184 offset:17408
	ds_read_b128 v[154:157], v184 offset:18432
	ds_read_b128 v[158:161], v184 offset:19456
	ds_read_b128 v[162:165], v184 offset:20480
	ds_read_b128 v[166:169], v184 offset:21504
	ds_read_b128 v[178:181], v184 offset:22528
	ds_read_b128 v[186:189], v184 offset:23552
	global_load_lds_dwordx4 v[234:235], off
	v_lshl_add_u64 v[236:237], s[2:3], 0, v[172:173]
	s_mov_b32 m0, s58
	s_nop 0
	global_load_lds_dwordx4 v[236:237], off
	s_barrier
	s_waitcnt lgkmcnt(0)
	s_waitcnt lgkmcnt(0)
	v_mfma_f32_16x16x32_bf16 v[94:97], v[130:133], v[146:149], v[94:97]
	v_mfma_f32_16x16x32_bf16 v[90:93], v[138:141], v[146:149], v[90:93]
	v_mfma_f32_16x16x32_bf16 v[86:89], v[130:133], v[154:157], v[86:89]
	v_mfma_f32_16x16x32_bf16 v[82:85], v[138:141], v[154:157], v[82:85]
	v_mfma_f32_16x16x32_bf16 v[78:81], v[130:133], v[162:165], v[78:81]
	v_mfma_f32_16x16x32_bf16 v[74:77], v[138:141], v[162:165], v[74:77]
	v_mfma_f32_16x16x32_bf16 v[70:73], v[130:133], v[178:181], v[70:73]
	v_mfma_f32_16x16x32_bf16 v[66:69], v[138:141], v[178:181], v[66:69]
	v_mfma_f32_16x16x32_bf16 v[94:97], v[134:137], v[150:153], v[94:97]
	v_mfma_f32_16x16x32_bf16 v[90:93], v[142:145], v[150:153], v[90:93]
	v_mfma_f32_16x16x32_bf16 v[86:89], v[134:137], v[158:161], v[86:89]
	v_mfma_f32_16x16x32_bf16 v[82:85], v[142:145], v[158:161], v[82:85]
	v_mfma_f32_16x16x32_bf16 v[78:81], v[134:137], v[166:169], v[78:81]
	v_mfma_f32_16x16x32_bf16 v[74:77], v[142:145], v[166:169], v[74:77]
	v_mfma_f32_16x16x32_bf16 v[70:73], v[134:137], v[186:189], v[70:73]
	v_mfma_f32_16x16x32_bf16 v[66:69], v[142:145], v[186:189], v[66:69]
	s_barrier
	s_add_u32 s12, s42, s18
	s_addc_u32 s13, s43, 0
	s_add_i32 s42, s92, s54
	v_lshl_add_u64 v[242:243], s[12:13], 0, v[170:171]
	s_mov_b32 m0, s42
	v_lshl_add_u64 v[244:245], s[12:13], 0, v[172:173]
	global_load_lds_dwordx4 v[242:243], off
	s_add_i32 m0, s42, 0x2000
	s_nop 0
	global_load_lds_dwordx4 v[244:245], off
	s_waitcnt vmcnt(6)
	s_barrier
	v_mfma_f32_16x16x32_bf16 v[30:33], v[190:193], v[146:149], v[30:33]
	v_mfma_f32_16x16x32_bf16 v[26:29], v[198:201], v[146:149], v[26:29]
	v_mfma_f32_16x16x32_bf16 v[22:25], v[190:193], v[154:157], v[22:25]
	v_mfma_f32_16x16x32_bf16 v[18:21], v[198:201], v[154:157], v[18:21]
	v_mfma_f32_16x16x32_bf16 v[14:17], v[190:193], v[162:165], v[14:17]
	v_mfma_f32_16x16x32_bf16 v[10:13], v[198:201], v[162:165], v[10:13]
	v_mfma_f32_16x16x32_bf16 v[6:9], v[190:193], v[178:181], v[6:9]
	v_mfma_f32_16x16x32_bf16 v[2:5], v[198:201], v[178:181], v[2:5]
	v_mfma_f32_16x16x32_bf16 v[30:33], v[194:197], v[150:153], v[30:33]
	v_mfma_f32_16x16x32_bf16 v[26:29], v[226:229], v[150:153], v[26:29]
	v_mfma_f32_16x16x32_bf16 v[22:25], v[194:197], v[158:161], v[22:25]
	v_mfma_f32_16x16x32_bf16 v[18:21], v[226:229], v[158:161], v[18:21]
	v_mfma_f32_16x16x32_bf16 v[14:17], v[194:197], v[166:169], v[14:17]
	v_mfma_f32_16x16x32_bf16 v[10:13], v[226:229], v[166:169], v[10:13]
	v_mfma_f32_16x16x32_bf16 v[6:9], v[194:197], v[186:189], v[6:9]
	v_mfma_f32_16x16x32_bf16 v[2:5], v[226:229], v[186:189], v[2:5]
	s_add_i32 s12, 0, 0x18000
	v_add_u32_e32 v142, s12, v183
	s_barrier
	ds_read_b128 v[130:133], v142
	ds_read_b128 v[134:137], v142 offset:1024
	ds_read_b128 v[138:141], v142 offset:2048
	ds_read_b128 v[142:145], v142 offset:3072
	s_add_u32 s2, s2, s18
	s_addc_u32 s3, s3, 0
	s_mov_b32 m0, s59
	v_lshl_add_u64 v[190:191], s[2:3], 0, v[170:171]
	ds_read_b128 v[146:149], v184 offset:32768
	ds_read_b128 v[150:153], v184 offset:33792
	ds_read_b128 v[154:157], v184 offset:34816
	ds_read_b128 v[158:161], v184 offset:35840
	ds_read_b128 v[162:165], v184 offset:36864
	ds_read_b128 v[166:169], v184 offset:37888
	ds_read_b128 v[178:181], v184 offset:38912
	ds_read_b128 v[186:189], v184 offset:39936
	global_load_lds_dwordx4 v[190:191], off
	v_lshl_add_u64 v[190:191], s[2:3], 0, v[172:173]
	s_mov_b32 m0, s77
	s_nop 0
	global_load_lds_dwordx4 v[190:191], off
	s_waitcnt lgkmcnt(8)
	s_barrier
	s_waitcnt lgkmcnt(0)
	s_waitcnt lgkmcnt(0)
	v_mfma_f32_16x16x32_bf16 v[126:129], v[130:133], v[146:149], v[126:129]
	v_mfma_f32_16x16x32_bf16 v[122:125], v[138:141], v[146:149], v[122:125]
	v_mfma_f32_16x16x32_bf16 v[118:121], v[130:133], v[154:157], v[118:121]
	v_mfma_f32_16x16x32_bf16 v[114:117], v[138:141], v[154:157], v[114:117]
	v_mfma_f32_16x16x32_bf16 v[110:113], v[130:133], v[162:165], v[110:113]
	v_mfma_f32_16x16x32_bf16 v[106:109], v[138:141], v[162:165], v[106:109]
	v_mfma_f32_16x16x32_bf16 v[102:105], v[130:133], v[178:181], v[102:105]
	v_mfma_f32_16x16x32_bf16 v[98:101], v[138:141], v[178:181], v[98:101]
	v_mfma_f32_16x16x32_bf16 v[126:129], v[134:137], v[150:153], v[126:129]
	v_mfma_f32_16x16x32_bf16 v[122:125], v[142:145], v[150:153], v[122:125]
	v_mfma_f32_16x16x32_bf16 v[118:121], v[134:137], v[158:161], v[118:121]
	v_mfma_f32_16x16x32_bf16 v[114:117], v[142:145], v[158:161], v[114:117]
	v_mfma_f32_16x16x32_bf16 v[110:113], v[134:137], v[166:169], v[110:113]
	v_mfma_f32_16x16x32_bf16 v[106:109], v[142:145], v[166:169], v[106:109]
	v_mfma_f32_16x16x32_bf16 v[102:105], v[134:137], v[186:189], v[102:105]
	v_mfma_f32_16x16x32_bf16 v[98:101], v[142:145], v[186:189], v[98:101]
	s_barrier
	s_add_i32 s2, 0, 0x1c000
	s_add_i32 s3, s12, s54
	v_add_u32_e32 v185, s2, v183
	v_lshl_add_u64 v[230:231], v[230:231], 0, s[20:21]
	s_mov_b32 m0, s3
	ds_read_b128 v[190:193], v185
	ds_read_b128 v[194:197], v185 offset:1024
	ds_read_b128 v[198:201], v185 offset:2048
	ds_read_b128 v[226:229], v185 offset:3072
	global_load_lds_dwordx4 v[230:231], off
	v_lshl_add_u64 v[230:231], v[232:233], 0, s[20:21]
	s_add_i32 m0, s3, 0x2000
	s_nop 0
	global_load_lds_dwordx4 v[230:231], off
	s_barrier
	s_waitcnt lgkmcnt(0)
	s_waitcnt lgkmcnt(0)
	v_mfma_f32_16x16x32_bf16 v[62:65], v[190:193], v[146:149], v[62:65]
	v_mfma_f32_16x16x32_bf16 v[58:61], v[198:201], v[146:149], v[58:61]
	v_mfma_f32_16x16x32_bf16 v[54:57], v[190:193], v[154:157], v[54:57]
	v_mfma_f32_16x16x32_bf16 v[50:53], v[198:201], v[154:157], v[50:53]
	v_mfma_f32_16x16x32_bf16 v[46:49], v[190:193], v[162:165], v[46:49]
	v_mfma_f32_16x16x32_bf16 v[42:45], v[198:201], v[162:165], v[42:45]
	v_mfma_f32_16x16x32_bf16 v[38:41], v[190:193], v[178:181], v[38:41]
	v_mfma_f32_16x16x32_bf16 v[34:37], v[198:201], v[178:181], v[34:37]
	v_mfma_f32_16x16x32_bf16 v[62:65], v[194:197], v[150:153], v[62:65]
	v_mfma_f32_16x16x32_bf16 v[58:61], v[226:229], v[150:153], v[58:61]
	v_mfma_f32_16x16x32_bf16 v[54:57], v[194:197], v[158:161], v[54:57]
	v_mfma_f32_16x16x32_bf16 v[50:53], v[226:229], v[158:161], v[50:53]
	v_mfma_f32_16x16x32_bf16 v[46:49], v[194:197], v[166:169], v[46:49]
	v_mfma_f32_16x16x32_bf16 v[42:45], v[226:229], v[166:169], v[42:45]
	v_mfma_f32_16x16x32_bf16 v[38:41], v[194:197], v[186:189], v[38:41]
	v_mfma_f32_16x16x32_bf16 v[34:37], v[226:229], v[186:189], v[34:37]
	s_mov_b32 m0, s80
	v_lshl_add_u64 v[230:231], v[234:235], 0, s[20:21]
	s_barrier
	ds_read_b128 v[146:149], v184 offset:49152
	ds_read_b128 v[150:153], v184 offset:50176
	ds_read_b128 v[154:157], v184 offset:51200
	ds_read_b128 v[158:161], v184 offset:52224
	ds_read_b128 v[162:165], v184 offset:53248
	ds_read_b128 v[166:169], v184 offset:54272
	ds_read_b128 v[178:181], v184 offset:55296
	ds_read_b128 v[186:189], v184 offset:56320
	global_load_lds_dwordx4 v[230:231], off
	v_lshl_add_u64 v[230:231], v[236:237], 0, s[20:21]
	s_mov_b32 m0, s81
	s_nop 0
	global_load_lds_dwordx4 v[230:231], off
	s_barrier
	s_waitcnt lgkmcnt(0)
	s_waitcnt lgkmcnt(0)
	v_mfma_f32_16x16x32_bf16 v[94:97], v[130:133], v[146:149], v[94:97]
	v_mfma_f32_16x16x32_bf16 v[90:93], v[138:141], v[146:149], v[90:93]
	v_mfma_f32_16x16x32_bf16 v[86:89], v[130:133], v[154:157], v[86:89]
	v_mfma_f32_16x16x32_bf16 v[82:85], v[138:141], v[154:157], v[82:85]
	v_mfma_f32_16x16x32_bf16 v[78:81], v[130:133], v[162:165], v[78:81]
	v_mfma_f32_16x16x32_bf16 v[74:77], v[138:141], v[162:165], v[74:77]
	v_mfma_f32_16x16x32_bf16 v[70:73], v[130:133], v[178:181], v[70:73]
	v_mfma_f32_16x16x32_bf16 v[66:69], v[138:141], v[178:181], v[66:69]
	v_mfma_f32_16x16x32_bf16 v[94:97], v[134:137], v[150:153], v[94:97]
	v_mfma_f32_16x16x32_bf16 v[90:93], v[142:145], v[150:153], v[90:93]
	v_mfma_f32_16x16x32_bf16 v[86:89], v[134:137], v[158:161], v[86:89]
	v_mfma_f32_16x16x32_bf16 v[82:85], v[142:145], v[158:161], v[82:85]
	v_mfma_f32_16x16x32_bf16 v[78:81], v[134:137], v[166:169], v[78:81]
	v_mfma_f32_16x16x32_bf16 v[74:77], v[142:145], v[166:169], v[74:77]
	v_mfma_f32_16x16x32_bf16 v[70:73], v[134:137], v[186:189], v[70:73]
	v_mfma_f32_16x16x32_bf16 v[66:69], v[142:145], v[186:189], v[66:69]
	s_barrier
	s_add_i32 s2, s2, s54
	v_lshl_add_u64 v[130:131], v[242:243], 0, s[20:21]
	s_mov_b32 m0, s2
	s_nop 0
	global_load_lds_dwordx4 v[130:131], off
	v_lshl_add_u64 v[130:131], v[244:245], 0, s[20:21]
	s_add_i32 m0, s2, 0x2000
	s_nop 0
	global_load_lds_dwordx4 v[130:131], off
	s_waitcnt vmcnt(6)
	s_barrier
	v_mfma_f32_16x16x32_bf16 v[30:33], v[190:193], v[146:149], v[30:33]
	v_mfma_f32_16x16x32_bf16 v[26:29], v[198:201], v[146:149], v[26:29]
	v_mfma_f32_16x16x32_bf16 v[22:25], v[190:193], v[154:157], v[22:25]
	v_mfma_f32_16x16x32_bf16 v[18:21], v[198:201], v[154:157], v[18:21]
	v_mfma_f32_16x16x32_bf16 v[14:17], v[190:193], v[162:165], v[14:17]
	v_mfma_f32_16x16x32_bf16 v[10:13], v[198:201], v[162:165], v[10:13]
	v_mfma_f32_16x16x32_bf16 v[6:9], v[190:193], v[178:181], v[6:9]
	v_mfma_f32_16x16x32_bf16 v[2:5], v[198:201], v[178:181], v[2:5]
	v_mfma_f32_16x16x32_bf16 v[30:33], v[194:197], v[150:153], v[30:33]
	v_mfma_f32_16x16x32_bf16 v[26:29], v[226:229], v[150:153], v[26:29]
	v_mfma_f32_16x16x32_bf16 v[22:25], v[194:197], v[158:161], v[22:25]
	v_mfma_f32_16x16x32_bf16 v[18:21], v[226:229], v[158:161], v[18:21]
	v_mfma_f32_16x16x32_bf16 v[14:17], v[194:197], v[166:169], v[14:17]
	v_mfma_f32_16x16x32_bf16 v[10:13], v[226:229], v[166:169], v[10:13]
	v_mfma_f32_16x16x32_bf16 v[6:9], v[194:197], v[186:189], v[6:9]
	v_mfma_f32_16x16x32_bf16 v[2:5], v[226:229], v[186:189], v[2:5]
	s_add_u32 s34, s34, 0x100
	s_addc_u32 s35, s35, 0
	s_add_u32 s89, s89, 0x100
	s_addc_u32 s90, s90, 0
	s_cmp_ge_i32 s91, s44
	s_mov_b32 s2, s91
	s_barrier
	s_cbranch_scc0 .LBB0_182
	s_cmp_lt_i32 s86, 64
	s_cselect_b64 s[34:35], -1, 0
	s_ashr_i32 s2, s45, 8
	s_ashr_i32 s3, s2, 31
	s_lshl_b64 s[2:3], s[2:3], 18
	s_add_u32 s2, s2, 0x3232000
	s_addc_u32 s3, s3, 0
	s_cmp_gt_i32 s86, 63
	s_cselect_b32 s12, 0x6000, 0
	s_cselect_b32 s45, s3, 0
	s_cselect_b32 s44, s2, 0
	s_add_u32 s12, s78, s12
	s_addc_u32 s13, s79, 0
	s_lshl_b32 s2, s87, 8
	s_ashr_i32 s3, s2, 31
	s_lshl_b64 s[2:3], s[2:3], 2
	s_add_u32 s12, s12, s2
	s_addc_u32 s13, s13, s3
	v_readlane_b32 s88, v254, 38
	s_add_u32 s42, s12, s88
	s_addc_u32 s43, s13, 0
	global_load_dwordx4 v[134:137], v0, s[42:43]
	global_load_dwordx4 v[130:133], v0, s[42:43] offset:64
	v_lshl_add_u32 v138, s86, 8, v182
	v_ashrrev_i32_e32 v139, 31, v138
	v_readlane_b32 s12, v252, 5
	v_lshlrev_b64 v[138:139], 12, v[138:139]
	v_readlane_b32 s13, v252, 6
	v_readlane_b32 s89, v254, 39
	s_and_b64 vcc, exec, s[34:35]
	v_lshl_add_u64 v[138:139], s[12:13], 0, v[138:139]
	v_lshl_add_u64 v[138:139], v[138:139], 0, s[2:3]
	v_lshl_add_u64 v[138:139], v[138:139], 0, s[88:89]
	v_lshl_add_u64 v[178:179], v[138:139], 0, v[0:1]
	v_lshl_add_u64 v[180:181], v[178:179], 0, s[22:23]
	v_readfirstlane_b32 s88, v178
	v_readfirstlane_b32 s89, v179
	v_and_b32_e32 v178, 15, v202
	v_bfe_u32 v179, v202, 4, 2
	v_lshlrev_b32_e32 v178, 12, v178
	v_lshl_or_b32 v178, v179, 4, v178
	s_mov_b32 s13, 0
	s_and_b64 vcc, exec, s[34:35]
	s_cbranch_vccz .Lre_nf
	v_readlane_b32 s2, v252, 2
	v_readlane_b32 s3, v255, 14
	v_readlane_b32 s12, v255, 12
	s_cmp_eq_u32 s2, 0x100
	s_cbranch_scc0 .Lre_nf
	s_cmp_eq_u32 s3, 5
	s_cbranch_scc1 .Lre_f
	s_cmp_eq_u32 s3, 8
	s_cbranch_scc0 .Lre_nf
.Lre_f:
	s_mov_b32 s13, 1

.Lfz_al:
	v_readlane_b32 s3, v255, 14
	v_readlane_b32 s2, v255, 12
	s_lshl_b32 s44, s2, 4
	s_or_b32 s44, s44, s3
	s_cmp_eq_u32 s44, 0x38
	s_cselect_b32 s45, 1, 0
	s_cmp_eq_u32 s3, 5
	s_cselect_b32 s44, 0, 1
	s_add_i32 s2, s2, s44
	v_readlane_b32 s12, v254, 21
	v_readlane_b32 s13, v254, 22
	v_readlane_b32 s42, v254, 54
	v_readlane_b32 s43, v254, 55
	s_cmp_eq_u32 s3, 5
	s_cselect_b32 s12, s12, s42
	s_cselect_b32 s13, s13, s43
	s_cselect_b32 s3, 0x3000, 0
	s_cmp_eq_u32 s45, 1
	s_cselect_b32 s12, s4, s12
	s_cselect_b32 s13, s5, s13
	s_cselect_b32 s2, 0, s2
	s_mov_b32 vcc_hi, s45
	s_lshr_b32 s44, s49, 6
	s_and_b32 s44, s44, 3
	s_lshl_b32 s44, s44, 7
	s_lshl_b32 s45, s87, 10
	s_add_i32 s44, s44, s45
	s_lshl_b32 s45, s2, 12
	s_add_i32 s45, s45, s44
	s_add_u32 s12, s12, s45
	s_addc_u32 s13, s13, 0
	v_readlane_b32 s42, v252, 11
	v_readlane_b32 s43, v252, 12
	s_mul_i32 s45, s2, 0xc000
	s_add_i32 s45, s45, s3
	s_add_i32 s45, s45, s44
	s_add_u32 s42, s42, s45
	s_addc_u32 s43, s43, 0
	s_add_u32 s44, s42, 0x1000
	s_addc_u32 s45, s43, 0
	v_lshlrev_b32_e32 v180, 4, v179
	s_nop 1
	s_cmp_eq_u32 vcc_hi, 1
	s_cbranch_scc1 .Lfz_pfin
	global_load_dwordx4 v[130:133], v180, s[12:13]
	global_load_dwordx4 v[146:149], v180, s[44:45]
	global_load_dwordx4 v[186:189], v180, s[42:43]
	global_load_dwordx4 v[134:137], v180, s[12:13] offset:64
	global_load_dwordx4 v[150:153], v180, s[44:45] offset:64
	global_load_dwordx4 v[190:193], v180, s[42:43] offset:64
	global_load_dwordx4 v[138:141], v180, s[12:13] offset:512
	global_load_dwordx4 v[154:157], v180, s[44:45] offset:512
	global_load_dwordx4 v[194:197], v180, s[42:43] offset:512
	global_load_dwordx4 v[142:145], v180, s[12:13] offset:576
	global_load_dwordx4 v[158:161], v180, s[44:45] offset:576
	global_load_dwordx4 v[198:201], v180, s[42:43] offset:576
	s_branch .Lfz_pdone
.Lfz_pfin:
	global_load_dwordx4 v[130:133], v180, s[12:13]
	global_load_dwordx4 v[146:149], v180, s[12:13]
	global_load_dwordx4 v[186:189], v180, s[12:13]
	global_load_dwordx4 v[134:137], v180, s[12:13] offset:64
	global_load_dwordx4 v[150:153], v180, s[12:13] offset:64
	global_load_dwordx4 v[190:193], v180, s[12:13] offset:64
	global_load_dwordx4 v[138:141], v180, s[12:13] offset:512
	global_load_dwordx4 v[154:157], v180, s[12:13] offset:512
	global_load_dwordx4 v[194:197], v180, s[12:13] offset:512
	global_load_dwordx4 v[142:145], v180, s[12:13] offset:576
	global_load_dwordx4 v[158:161], v180, s[12:13] offset:576
	global_load_dwordx4 v[198:201], v180, s[12:13] offset:576
.Lfz_pdone:
	v_mul_f32_e32 v226, v126, v126
	v_fmac_f32_e32 v226, v127, v127
	v_fmac_f32_e32 v226, v128, v128
	v_fmac_f32_e32 v226, v129, v129
	v_fmac_f32_e32 v226, v122, v122
	v_fmac_f32_e32 v226, v123, v123
	v_fmac_f32_e32 v226, v124, v124
	v_fmac_f32_e32 v226, v125, v125
	v_fmac_f32_e32 v226, v62, v62
	v_fmac_f32_e32 v226, v63, v63
	v_fmac_f32_e32 v226, v64, v64
	v_fmac_f32_e32 v226, v65, v65
	v_fmac_f32_e32 v226, v58, v58
	v_fmac_f32_e32 v226, v59, v59
	v_fmac_f32_e32 v226, v60, v60
	v_fmac_f32_e32 v226, v61, v61
	v_mul_f32_e32 v227, v118, v118
	v_fmac_f32_e32 v227, v119, v119
	v_fmac_f32_e32 v227, v120, v120
	v_fmac_f32_e32 v227, v121, v121
	v_fmac_f32_e32 v227, v114, v114
	v_fmac_f32_e32 v227, v115, v115
	v_fmac_f32_e32 v227, v116, v116
	v_fmac_f32_e32 v227, v117, v117
	v_fmac_f32_e32 v227, v54, v54
	v_fmac_f32_e32 v227, v55, v55
	v_fmac_f32_e32 v227, v56, v56
	v_fmac_f32_e32 v227, v57, v57
	v_fmac_f32_e32 v227, v50, v50
	v_fmac_f32_e32 v227, v51, v51
	v_fmac_f32_e32 v227, v52, v52
	v_fmac_f32_e32 v227, v53, v53
	v_mul_f32_e32 v228, v110, v110
	v_fmac_f32_e32 v228, v111, v111
	v_fmac_f32_e32 v228, v112, v112
	v_fmac_f32_e32 v228, v113, v113
	v_fmac_f32_e32 v228, v106, v106
	v_fmac_f32_e32 v228, v107, v107
	v_fmac_f32_e32 v228, v108, v108
	v_fmac_f32_e32 v228, v109, v109
	v_fmac_f32_e32 v228, v46, v46
	v_fmac_f32_e32 v228, v47, v47
	v_fmac_f32_e32 v228, v48, v48
	v_fmac_f32_e32 v228, v49, v49
	v_fmac_f32_e32 v228, v42, v42
	v_fmac_f32_e32 v228, v43, v43
	v_fmac_f32_e32 v228, v44, v44
	v_fmac_f32_e32 v228, v45, v45
	v_mul_f32_e32 v229, v102, v102
	v_fmac_f32_e32 v229, v103, v103
	v_fmac_f32_e32 v229, v104, v104
	v_fmac_f32_e32 v229, v105, v105
	v_fmac_f32_e32 v229, v98, v98
	v_fmac_f32_e32 v229, v99, v99
	v_fmac_f32_e32 v229, v100, v100
	v_fmac_f32_e32 v229, v101, v101
	v_fmac_f32_e32 v229, v38, v38
	v_fmac_f32_e32 v229, v39, v39
	v_fmac_f32_e32 v229, v40, v40
	v_fmac_f32_e32 v229, v41, v41
	v_fmac_f32_e32 v229, v34, v34
	v_fmac_f32_e32 v229, v35, v35
	v_fmac_f32_e32 v229, v36, v36
	v_fmac_f32_e32 v229, v37, v37
	v_mul_f32_e32 v230, v94, v94
	v_fmac_f32_e32 v230, v95, v95
	v_fmac_f32_e32 v230, v96, v96
	v_fmac_f32_e32 v230, v97, v97
	v_fmac_f32_e32 v230, v90, v90
	v_fmac_f32_e32 v230, v91, v91
	v_fmac_f32_e32 v230, v92, v92
	v_fmac_f32_e32 v230, v93, v93
	v_fmac_f32_e32 v230, v30, v30
	v_fmac_f32_e32 v230, v31, v31
	v_fmac_f32_e32 v230, v32, v32
	v_fmac_f32_e32 v230, v33, v33
	v_fmac_f32_e32 v230, v26, v26
	v_fmac_f32_e32 v230, v27, v27
	v_fmac_f32_e32 v230, v28, v28
	v_fmac_f32_e32 v230, v29, v29
	v_mul_f32_e32 v231, v86, v86
	v_fmac_f32_e32 v231, v87, v87
	v_fmac_f32_e32 v231, v88, v88
	v_fmac_f32_e32 v231, v89, v89
	v_fmac_f32_e32 v231, v82, v82
	v_fmac_f32_e32 v231, v83, v83
	v_fmac_f32_e32 v231, v84, v84
	v_fmac_f32_e32 v231, v85, v85
	v_fmac_f32_e32 v231, v22, v22
	v_fmac_f32_e32 v231, v23, v23
	v_fmac_f32_e32 v231, v24, v24
	v_fmac_f32_e32 v231, v25, v25
	v_fmac_f32_e32 v231, v18, v18
	v_fmac_f32_e32 v231, v19, v19
	v_fmac_f32_e32 v231, v20, v20
	v_fmac_f32_e32 v231, v21, v21
	v_mul_f32_e32 v232, v78, v78
	v_fmac_f32_e32 v232, v79, v79
	v_fmac_f32_e32 v232, v80, v80
	v_fmac_f32_e32 v232, v81, v81
	v_fmac_f32_e32 v232, v74, v74
	v_fmac_f32_e32 v232, v75, v75
	v_fmac_f32_e32 v232, v76, v76
	v_fmac_f32_e32 v232, v77, v77
	v_fmac_f32_e32 v232, v14, v14
	v_fmac_f32_e32 v232, v15, v15
	v_fmac_f32_e32 v232, v16, v16
	v_fmac_f32_e32 v232, v17, v17
	v_fmac_f32_e32 v232, v10, v10
	v_fmac_f32_e32 v232, v11, v11
	v_fmac_f32_e32 v232, v12, v12
	v_fmac_f32_e32 v232, v13, v13
	v_mul_f32_e32 v233, v70, v70
	v_fmac_f32_e32 v233, v71, v71
	v_fmac_f32_e32 v233, v72, v72
	v_fmac_f32_e32 v233, v73, v73
	v_fmac_f32_e32 v233, v66, v66
	v_fmac_f32_e32 v233, v67, v67
	v_fmac_f32_e32 v233, v68, v68
	v_fmac_f32_e32 v233, v69, v69
	v_fmac_f32_e32 v233, v6, v6
	v_fmac_f32_e32 v233, v7, v7
	v_fmac_f32_e32 v233, v8, v8
	v_fmac_f32_e32 v233, v9, v9
	v_fmac_f32_e32 v233, v2, v2
	v_fmac_f32_e32 v233, v3, v3
	v_fmac_f32_e32 v233, v4, v4
	v_fmac_f32_e32 v233, v5, v5
	v_mov_b32_e32 v234, v226
	v_mov_b32_e32 v235, v227
	v_mov_b32_e32 v236, v228
	v_mov_b32_e32 v237, v229
	v_mov_b32_e32 v242, v230
	v_mov_b32_e32 v243, v231
	v_mov_b32_e32 v244, v232
	v_mov_b32_e32 v245, v233
	v_permlane32_swap_b32_e32 v226, v234
	v_permlane32_swap_b32_e32 v227, v235
	v_permlane32_swap_b32_e32 v228, v236
	v_permlane32_swap_b32_e32 v229, v237
	v_permlane32_swap_b32_e32 v230, v242
	v_permlane32_swap_b32_e32 v231, v243
	v_permlane32_swap_b32_e32 v232, v244
	v_permlane32_swap_b32_e32 v233, v245
	v_add_f32_e32 v226, v226, v234
	v_add_f32_e32 v227, v227, v235
	v_add_f32_e32 v228, v228, v236
	v_add_f32_e32 v229, v229, v237
	v_add_f32_e32 v230, v230, v242
	v_add_f32_e32 v231, v231, v243
	v_add_f32_e32 v232, v232, v244
	v_add_f32_e32 v233, v233, v245
	v_mov_b32_e32 v234, v226
	v_mov_b32_e32 v235, v227
	v_mov_b32_e32 v236, v228
	v_mov_b32_e32 v237, v229
	v_mov_b32_e32 v242, v230
	v_mov_b32_e32 v243, v231
	v_mov_b32_e32 v244, v232
	v_mov_b32_e32 v245, v233
	v_permlane16_swap_b32_e32 v226, v234
	v_permlane16_swap_b32_e32 v227, v235
	v_permlane16_swap_b32_e32 v228, v236
	v_permlane16_swap_b32_e32 v229, v237
	v_permlane16_swap_b32_e32 v230, v242
	v_permlane16_swap_b32_e32 v231, v243
	v_permlane16_swap_b32_e32 v232, v244
	v_permlane16_swap_b32_e32 v233, v245
	v_add_f32_e32 v226, v226, v234
	v_add_f32_e32 v227, v227, v235
	v_add_f32_e32 v228, v228, v236
	v_add_f32_e32 v229, v229, v237
	v_add_f32_e32 v230, v230, v242
	v_add_f32_e32 v231, v231, v243
	v_add_f32_e32 v232, v232, v244
	v_add_f32_e32 v233, v233, v245
	s_lshr_b32 s2, s49, 6
	s_and_b32 s3, s2, 3
	s_lshr_b32 s2, s2, 2
	s_lshl_b32 s2, s2, 10
	s_lshl_b32 s3, s3, 2
	s_add_i32 s2, s2, s3
	s_add_i32 s2, s2, 0x21400
	v_and_b32_e32 v181, 15, v202
	v_lshl_add_u32 v181, v181, 4, s2
	s_mov_b64 s[34:35], exec
	s_mov_b64 exec, 0xffff
	ds_write_b32 v181, v226
	ds_write_b32 v181, v227 offset:256
	ds_write_b32 v181, v228 offset:512
	ds_write_b32 v181, v229 offset:768
	ds_write_b32 v181, v230 offset:2048
	ds_write_b32 v181, v231 offset:2304
	ds_write_b32 v181, v232 offset:2560
	ds_write_b32 v181, v233 offset:2816
	s_mov_b64 exec, s[34:35]
	s_cmpk_gt_u32 s49, 0xff
	s_cbranch_scc0 .Lfz_w03a
	v_readlane_b32 s44, v255, 14
	v_readlane_b32 s45, v255, 12
	s_lshl_b32 s45, s45, 4
	s_or_b32 s44, s44, s45
	s_cmp_eq_u32 s44, 0x38
	s_cbranch_scc1 .Lfz_nh1
	s_mov_b32 s2, s88
	s_mov_b32 s3, s89
	global_store_dwordx4 v178, v[126:129], s[2:3] offset:0
	global_store_dwordx4 v178, v[122:125], s[2:3] offset:64
	s_add_u32 s2, s2, 0x10000
	s_addc_u32 s3, s3, 0
	global_store_dwordx4 v178, v[118:121], s[2:3] offset:0
	global_store_dwordx4 v178, v[114:117], s[2:3] offset:64
	s_add_u32 s2, s2, 0x10000
	s_addc_u32 s3, s3, 0
	global_store_dwordx4 v178, v[110:113], s[2:3] offset:0
	global_store_dwordx4 v178, v[106:109], s[2:3] offset:64
	s_add_u32 s2, s2, 0x10000
	s_addc_u32 s3, s3, 0
	global_store_dwordx4 v178, v[102:105], s[2:3] offset:0
	global_store_dwordx4 v178, v[98:101], s[2:3] offset:64
	s_add_u32 s2, s2, 0x50000
	s_addc_u32 s3, s3, 0
	global_store_dwordx4 v178, v[94:97], s[2:3] offset:0
	global_store_dwordx4 v178, v[90:93], s[2:3] offset:64
	s_add_u32 s2, s2, 0x10000
	s_addc_u32 s3, s3, 0
	global_store_dwordx4 v178, v[86:89], s[2:3] offset:0
	global_store_dwordx4 v178, v[82:85], s[2:3] offset:64
	s_add_u32 s2, s2, 0x10000
	s_addc_u32 s3, s3, 0
	global_store_dwordx4 v178, v[78:81], s[2:3] offset:0
	global_store_dwordx4 v178, v[74:77], s[2:3] offset:64
	s_add_u32 s2, s2, 0x10000
	s_addc_u32 s3, s3, 0
	global_store_dwordx4 v178, v[70:73], s[2:3] offset:0
	global_store_dwordx4 v178, v[66:69], s[2:3] offset:64
	s_mov_b32 s2, s88
	s_mov_b32 s3, s89
	global_store_dwordx4 v178, v[62:65], s[2:3] offset:512
	global_store_dwordx4 v178, v[58:61], s[2:3] offset:576
	s_add_u32 s2, s2, 0x10000
	s_addc_u32 s3, s3, 0
	global_store_dwordx4 v178, v[54:57], s[2:3] offset:512
	global_store_dwordx4 v178, v[50:53], s[2:3] offset:576
	s_add_u32 s2, s2, 0x10000
	s_addc_u32 s3, s3, 0
	global_store_dwordx4 v178, v[46:49], s[2:3] offset:512
	global_store_dwordx4 v178, v[42:45], s[2:3] offset:576
	s_add_u32 s2, s2, 0x10000
	s_addc_u32 s3, s3, 0
	global_store_dwordx4 v178, v[38:41], s[2:3] offset:512
	global_store_dwordx4 v178, v[34:37], s[2:3] offset:576
	s_add_u32 s2, s2, 0x50000
	s_addc_u32 s3, s3, 0
	global_store_dwordx4 v178, v[30:33], s[2:3] offset:512
	global_store_dwordx4 v178, v[26:29], s[2:3] offset:576
	s_add_u32 s2, s2, 0x10000
	s_addc_u32 s3, s3, 0
	global_store_dwordx4 v178, v[22:25], s[2:3] offset:512
	global_store_dwordx4 v178, v[18:21], s[2:3] offset:576
	s_add_u32 s2, s2, 0x10000
	s_addc_u32 s3, s3, 0
	global_store_dwordx4 v178, v[14:17], s[2:3] offset:512
	global_store_dwordx4 v178, v[10:13], s[2:3] offset:576
	s_add_u32 s2, s2, 0x10000
	s_addc_u32 s3, s3, 0
	global_store_dwordx4 v178, v[6:9], s[2:3] offset:512
	global_store_dwordx4 v178, v[2:5], s[2:3] offset:576
	s_waitcnt vmcnt(32) lgkmcnt(0)
	s_branch .Lfz_b1
.Lfz_nh1:
	s_waitcnt vmcnt(0) lgkmcnt(0)
	s_branch .Lfz_b1

.Lfz_b1:
	s_barrier
	v_readlane_b32 s44, v255, 14
	v_readlane_b32 s45, v255, 12
	s_lshl_b32 s45, s45, 4
	s_or_b32 s44, s44, s45
	s_cmp_eq_u32 s44, 0x38
	s_cbranch_scc1 .Lfz_mfin
	v_add_f32_e32 v146, 1.0, v146
	v_add_f32_e32 v147, 1.0, v147
	v_add_f32_e32 v148, 1.0, v148
	v_add_f32_e32 v149, 1.0, v149
	v_add_f32_e32 v150, 1.0, v150
	v_add_f32_e32 v151, 1.0, v151
	v_add_f32_e32 v152, 1.0, v152
	v_add_f32_e32 v153, 1.0, v153
	v_add_f32_e32 v154, 1.0, v154
	v_add_f32_e32 v155, 1.0, v155
	v_add_f32_e32 v156, 1.0, v156
	v_add_f32_e32 v157, 1.0, v157
	v_add_f32_e32 v158, 1.0, v158
	v_add_f32_e32 v159, 1.0, v159
	v_add_f32_e32 v160, 1.0, v160
	v_add_f32_e32 v161, 1.0, v161
	v_mul_f32_e32 v130, v130, v146
	v_mul_f32_e32 v131, v131, v147
	v_mul_f32_e32 v132, v132, v148
	v_mul_f32_e32 v133, v133, v149
	v_mul_f32_e32 v134, v134, v150
	v_mul_f32_e32 v135, v135, v151
	v_mul_f32_e32 v136, v136, v152
	v_mul_f32_e32 v137, v137, v153
	v_mul_f32_e32 v138, v138, v154
	v_mul_f32_e32 v139, v139, v155
	v_mul_f32_e32 v140, v140, v156
	v_mul_f32_e32 v141, v141, v157
	v_mul_f32_e32 v142, v142, v158
	v_mul_f32_e32 v143, v143, v159
	v_mul_f32_e32 v144, v144, v160
	v_mul_f32_e32 v145, v145, v161
	s_branch .Lfz_mdone
.Lfz_mfin:
	v_mov_b32_e32 v186, 0
	v_mov_b32_e32 v187, 0
	v_mov_b32_e32 v188, 0
	v_mov_b32_e32 v189, 0
	v_mov_b32_e32 v190, 0
	v_mov_b32_e32 v191, 0
	v_mov_b32_e32 v192, 0
	v_mov_b32_e32 v193, 0
	v_mov_b32_e32 v194, 0
	v_mov_b32_e32 v195, 0
	v_mov_b32_e32 v196, 0
	v_mov_b32_e32 v197, 0
	v_mov_b32_e32 v198, 0
	v_mov_b32_e32 v199, 0
	v_mov_b32_e32 v200, 0
	v_mov_b32_e32 v201, 0
.Lfz_mdone:
	s_lshl_b32 s2, s86, 12
	s_add_u32 s2, s8, s2
	s_addc_u32 s3, s9, 0
	s_add_u32 s2, s2, 0x15234000
	s_addc_u32 s3, s3, 0
	s_lshl_b32 s12, s87, 10
	s_add_u32 s12, s2, s12
	s_addc_u32 s13, s3, 0
	s_lshl_b32 s42, s86, 5
	s_add_u32 s42, s8, s42
	s_addc_u32 s43, s9, 0
	s_add_u32 s42, s42, 0x3600
	s_addc_u32 s43, s43, 0
	s_cmpk_gt_u32 s49, 0xff
	s_cbranch_scc1 .Lfz_p1
	s_movk_i32 s44, 0x1400
	s_add_i32 s44, s44, 0x20000
	v_lshl_add_u32 v154, v202, 4, s44
	v_lshlrev_b32_e32 v155, 2, v202
	ds_read_b128 v[146:149], v154
	s_waitcnt lgkmcnt(0)
	v_add_f32_e32 v146, v146, v147
	v_add_f32_e32 v148, v148, v149
	v_add_f32_e32 v146, v146, v148
	global_store_dword v155, v146, s[12:13] sc0 sc1
	s_waitcnt vmcnt(0)

.Lfz_arr:
	s_barrier
	s_cmpk_gt_u32 s49, 0xff
	s_cbranch_scc1 .Lfz_p2
	global_load_dword v146, v155, s[2:3] sc0 sc1
	global_load_dword v147, v155, s[2:3] offset:1024 sc0 sc1
	global_load_dword v148, v155, s[2:3] offset:2048 sc0 sc1
	global_load_dword v149, v155, s[2:3] offset:3072 sc0 sc1
	v_mov_b32_e32 v150, 0x3a800000
	s_movk_i32 s44, 0x2400
	s_add_i32 s44, s44, 0x20000
	v_add_u32_e32 v151, s44, v155
	s_waitcnt vmcnt(0)
	v_add_f32_e32 v146, v146, v147
	v_add_f32_e32 v148, v148, v149
	v_add_f32_e32 v146, v146, v148
	v_fma_f32 v146, v146, v150, v203
	v_rsq_f32_e32 v146, v146
	s_nop 0
	ds_write_b32 v151, v146
	v_readlane_b32 s44, v255, 14
	v_readlane_b32 s45, v255, 12
	s_lshl_b32 s45, s45, 4
	s_or_b32 s44, s44, s45
	s_cmp_eq_u32 s44, 0x38
	s_cbranch_scc1 .Lfz_nh2
	s_mov_b32 s2, s88
	s_mov_b32 s3, s89
	global_store_dwordx4 v178, v[126:129], s[2:3] offset:0
	global_store_dwordx4 v178, v[122:125], s[2:3] offset:64
	s_add_u32 s2, s2, 0x10000
	s_addc_u32 s3, s3, 0
	global_store_dwordx4 v178, v[118:121], s[2:3] offset:0
	global_store_dwordx4 v178, v[114:117], s[2:3] offset:64
	s_add_u32 s2, s2, 0x10000
	s_addc_u32 s3, s3, 0
	global_store_dwordx4 v178, v[110:113], s[2:3] offset:0
	global_store_dwordx4 v178, v[106:109], s[2:3] offset:64
	s_add_u32 s2, s2, 0x10000
	s_addc_u32 s3, s3, 0
	global_store_dwordx4 v178, v[102:105], s[2:3] offset:0
	global_store_dwordx4 v178, v[98:101], s[2:3] offset:64
	s_add_u32 s2, s2, 0x50000
	s_addc_u32 s3, s3, 0
	global_store_dwordx4 v178, v[94:97], s[2:3] offset:0
	global_store_dwordx4 v178, v[90:93], s[2:3] offset:64
	s_add_u32 s2, s2, 0x10000
	s_addc_u32 s3, s3, 0
	global_store_dwordx4 v178, v[86:89], s[2:3] offset:0
	global_store_dwordx4 v178, v[82:85], s[2:3] offset:64
	s_add_u32 s2, s2, 0x10000
	s_addc_u32 s3, s3, 0
	global_store_dwordx4 v178, v[78:81], s[2:3] offset:0
	global_store_dwordx4 v178, v[74:77], s[2:3] offset:64
	s_add_u32 s2, s2, 0x10000
	s_addc_u32 s3, s3, 0
	global_store_dwordx4 v178, v[70:73], s[2:3] offset:0
	global_store_dwordx4 v178, v[66:69], s[2:3] offset:64
	s_mov_b32 s2, s88
	s_mov_b32 s3, s89
	global_store_dwordx4 v178, v[62:65], s[2:3] offset:512
	global_store_dwordx4 v178, v[58:61], s[2:3] offset:576
	s_add_u32 s2, s2, 0x10000
	s_addc_u32 s3, s3, 0
	global_store_dwordx4 v178, v[54:57], s[2:3] offset:512
	global_store_dwordx4 v178, v[50:53], s[2:3] offset:576
	s_add_u32 s2, s2, 0x10000
	s_addc_u32 s3, s3, 0
	global_store_dwordx4 v178, v[46:49], s[2:3] offset:512
	global_store_dwordx4 v178, v[42:45], s[2:3] offset:576
	s_add_u32 s2, s2, 0x10000
	s_addc_u32 s3, s3, 0
	global_store_dwordx4 v178, v[38:41], s[2:3] offset:512
	global_store_dwordx4 v178, v[34:37], s[2:3] offset:576
	s_add_u32 s2, s2, 0x50000
	s_addc_u32 s3, s3, 0
	global_store_dwordx4 v178, v[30:33], s[2:3] offset:512
	global_store_dwordx4 v178, v[26:29], s[2:3] offset:576
	s_add_u32 s2, s2, 0x10000
	s_addc_u32 s3, s3, 0
	global_store_dwordx4 v178, v[22:25], s[2:3] offset:512
	global_store_dwordx4 v178, v[18:21], s[2:3] offset:576
	s_add_u32 s2, s2, 0x10000
	s_addc_u32 s3, s3, 0
	global_store_dwordx4 v178, v[14:17], s[2:3] offset:512
	global_store_dwordx4 v178, v[10:13], s[2:3] offset:576
	s_add_u32 s2, s2, 0x10000
	s_addc_u32 s3, s3, 0
	global_store_dwordx4 v178, v[6:9], s[2:3] offset:512
	global_store_dwordx4 v178, v[2:5], s[2:3] offset:576

.Lfz_p2:
	s_barrier
	s_lshr_b32 s2, s49, 8
	s_lshl_b32 s3, s2, 8
	s_movk_i32 s44, 0x2400
	s_add_i32 s44, s44, 0x20000
	s_add_i32 s3, s3, s44
	v_and_b32_e32 v156, 15, v202
	v_lshl_add_u32 v156, v156, 2, s3
	ds_read_b32 v162, v156
	ds_read_b32 v163, v156 offset:64
	ds_read_b32 v164, v156 offset:128
	ds_read_b32 v165, v156 offset:192
	ds_read_b32 v166, v156 offset:512
	ds_read_b32 v167, v156 offset:576
	ds_read_b32 v168, v156 offset:640
	ds_read_b32 v169, v156 offset:704
	s_waitcnt lgkmcnt(0)
	v_readlane_b32 s44, v255, 14
	v_readlane_b32 s45, v255, 12
	s_lshl_b32 s45, s45, 4
	s_or_b32 s44, s44, s45
	s_cmp_eq_u32 s44, 0x38
	s_cbranch_scc1 .Lfz_ofin
	v_and_b32_e32 v157, 15, v202
	v_lshlrev_b32_e32 v157, 11, v157
	v_lshl_or_b32 v157, v179, 3, v157
	v_readlane_b32 s44, v252, 20
	v_readlane_b32 s45, v252, 21
	s_lshl_b32 s3, s86, 8
	s_lshl_b32 s2, s2, 6
	s_add_i32 s3, s3, s2
	s_add_i32 s3, s3, 1
	s_lshl_b32 s3, s3, 11
	s_lshr_b32 s2, s49, 6
	s_and_b32 s2, s2, 3
	s_lshl_b32 s2, s2, 6
	s_lshl_b32 s12, s87, 9
	s_add_i32 s2, s2, s12
	s_add_i32 s3, s3, s2
	s_add_u32 s44, s44, s3
	s_addc_u32 s45, s45, 0
	v_mul_f32_e32 v146, v162, v126
	v_mul_f32_e32 v147, v162, v127
	v_mul_f32_e32 v148, v162, v128
	v_mul_f32_e32 v149, v162, v129
	v_fma_f32 v146, v146, v130, v186
	v_fma_f32 v147, v147, v131, v187
	v_fma_f32 v148, v148, v132, v188
	v_fma_f32 v149, v149, v133, v189
	v_cvt_pk_bf16_f32 v150, v146, v147
	v_cvt_pk_bf16_f32 v151, v148, v149
	global_store_dwordx2 v157, v[150:151], s[44:45]
	v_mul_f32_e32 v146, v162, v122
	v_mul_f32_e32 v147, v162, v123
	v_mul_f32_e32 v148, v162, v124
	v_mul_f32_e32 v149, v162, v125
	v_fma_f32 v146, v146, v134, v190
	v_fma_f32 v147, v147, v135, v191
	v_fma_f32 v148, v148, v136, v192
	v_fma_f32 v149, v149, v137, v193
	v_cvt_pk_bf16_f32 v152, v146, v147
	v_cvt_pk_bf16_f32 v153, v148, v149
	global_store_dwordx2 v157, v[152:153], s[44:45] offset:32
	v_mul_f32_e32 v146, v162, v62
	v_mul_f32_e32 v147, v162, v63
	v_mul_f32_e32 v148, v162, v64
	v_mul_f32_e32 v149, v162, v65
	v_fma_f32 v146, v146, v138, v194
	v_fma_f32 v147, v147, v139, v195
	v_fma_f32 v148, v148, v140, v196
	v_fma_f32 v149, v149, v141, v197
	v_cvt_pk_bf16_f32 v154, v146, v147
	v_cvt_pk_bf16_f32 v155, v148, v149
	global_store_dwordx2 v157, v[154:155], s[44:45] offset:256
	v_mul_f32_e32 v146, v162, v58
	v_mul_f32_e32 v147, v162, v59
	v_mul_f32_e32 v148, v162, v60
	v_mul_f32_e32 v149, v162, v61
	v_fma_f32 v146, v146, v142, v198
	v_fma_f32 v147, v147, v143, v199
	v_fma_f32 v148, v148, v144, v200
	v_fma_f32 v149, v149, v145, v201
	v_cvt_pk_bf16_f32 v158, v146, v147
	v_cvt_pk_bf16_f32 v159, v148, v149
	global_store_dwordx2 v157, v[158:159], s[44:45] offset:288
	s_add_u32 s44, s44, 0x8000
	s_addc_u32 s45, s45, 0
	v_mul_f32_e32 v146, v163, v118
	v_mul_f32_e32 v147, v163, v119
	v_mul_f32_e32 v148, v163, v120
	v_mul_f32_e32 v149, v163, v121
	v_fma_f32 v146, v146, v130, v186
	v_fma_f32 v147, v147, v131, v187
	v_fma_f32 v148, v148, v132, v188
	v_fma_f32 v149, v149, v133, v189
	v_cvt_pk_bf16_f32 v150, v146, v147
	v_cvt_pk_bf16_f32 v151, v148, v149
	global_store_dwordx2 v157, v[150:151], s[44:45]
	v_mul_f32_e32 v146, v163, v114
	v_mul_f32_e32 v147, v163, v115
	v_mul_f32_e32 v148, v163, v116
	v_mul_f32_e32 v149, v163, v117
	v_fma_f32 v146, v146, v134, v190
	v_fma_f32 v147, v147, v135, v191
	v_fma_f32 v148, v148, v136, v192
	v_fma_f32 v149, v149, v137, v193
	v_cvt_pk_bf16_f32 v152, v146, v147
	v_cvt_pk_bf16_f32 v153, v148, v149
	global_store_dwordx2 v157, v[152:153], s[44:45] offset:32
	v_mul_f32_e32 v146, v163, v54
	v_mul_f32_e32 v147, v163, v55
	v_mul_f32_e32 v148, v163, v56
	v_mul_f32_e32 v149, v163, v57
	v_fma_f32 v146, v146, v138, v194
	v_fma_f32 v147, v147, v139, v195
	v_fma_f32 v148, v148, v140, v196
	v_fma_f32 v149, v149, v141, v197
	v_cvt_pk_bf16_f32 v154, v146, v147
	v_cvt_pk_bf16_f32 v155, v148, v149
	global_store_dwordx2 v157, v[154:155], s[44:45] offset:256
	v_mul_f32_e32 v146, v163, v50
	v_mul_f32_e32 v147, v163, v51
	v_mul_f32_e32 v148, v163, v52
	v_mul_f32_e32 v149, v163, v53
	v_fma_f32 v146, v146, v142, v198
	v_fma_f32 v147, v147, v143, v199
	v_fma_f32 v148, v148, v144, v200
	v_fma_f32 v149, v149, v145, v201
	v_cvt_pk_bf16_f32 v158, v146, v147
	v_cvt_pk_bf16_f32 v159, v148, v149
	global_store_dwordx2 v157, v[158:159], s[44:45] offset:288
	s_add_u32 s44, s44, 0x8000
	s_addc_u32 s45, s45, 0
	v_mul_f32_e32 v146, v164, v110
	v_mul_f32_e32 v147, v164, v111
	v_mul_f32_e32 v148, v164, v112
	v_mul_f32_e32 v149, v164, v113
	v_fma_f32 v146, v146, v130, v186
	v_fma_f32 v147, v147, v131, v187
	v_fma_f32 v148, v148, v132, v188
	v_fma_f32 v149, v149, v133, v189
	v_cvt_pk_bf16_f32 v150, v146, v147
	v_cvt_pk_bf16_f32 v151, v148, v149
	global_store_dwordx2 v157, v[150:151], s[44:45]
	v_mul_f32_e32 v146, v164, v106
	v_mul_f32_e32 v147, v164, v107
	v_mul_f32_e32 v148, v164, v108
	v_mul_f32_e32 v149, v164, v109
	v_fma_f32 v146, v146, v134, v190
	v_fma_f32 v147, v147, v135, v191
	v_fma_f32 v148, v148, v136, v192
	v_fma_f32 v149, v149, v137, v193
	v_cvt_pk_bf16_f32 v152, v146, v147
	v_cvt_pk_bf16_f32 v153, v148, v149
	global_store_dwordx2 v157, v[152:153], s[44:45] offset:32
	v_mul_f32_e32 v146, v164, v46
	v_mul_f32_e32 v147, v164, v47
	v_mul_f32_e32 v148, v164, v48
	v_mul_f32_e32 v149, v164, v49
	v_fma_f32 v146, v146, v138, v194
	v_fma_f32 v147, v147, v139, v195
	v_fma_f32 v148, v148, v140, v196
	v_fma_f32 v149, v149, v141, v197
	v_cvt_pk_bf16_f32 v154, v146, v147
	v_cvt_pk_bf16_f32 v155, v148, v149
	global_store_dwordx2 v157, v[154:155], s[44:45] offset:256
	v_mul_f32_e32 v146, v164, v42
	v_mul_f32_e32 v147, v164, v43
	v_mul_f32_e32 v148, v164, v44
	v_mul_f32_e32 v149, v164, v45
	v_fma_f32 v146, v146, v142, v198
	v_fma_f32 v147, v147, v143, v199
	v_fma_f32 v148, v148, v144, v200
	v_fma_f32 v149, v149, v145, v201
	v_cvt_pk_bf16_f32 v158, v146, v147
	v_cvt_pk_bf16_f32 v159, v148, v149
	global_store_dwordx2 v157, v[158:159], s[44:45] offset:288
	s_add_u32 s44, s44, 0x8000
	s_addc_u32 s45, s45, 0
	v_mul_f32_e32 v146, v165, v102
	v_mul_f32_e32 v147, v165, v103
	v_mul_f32_e32 v148, v165, v104
	v_mul_f32_e32 v149, v165, v105
	v_fma_f32 v146, v146, v130, v186
	v_fma_f32 v147, v147, v131, v187
	v_fma_f32 v148, v148, v132, v188
	v_fma_f32 v149, v149, v133, v189
	v_cvt_pk_bf16_f32 v150, v146, v147
	v_cvt_pk_bf16_f32 v151, v148, v149
	global_store_dwordx2 v157, v[150:151], s[44:45]
	v_mul_f32_e32 v146, v165, v98
	v_mul_f32_e32 v147, v165, v99
	v_mul_f32_e32 v148, v165, v100
	v_mul_f32_e32 v149, v165, v101
	v_fma_f32 v146, v146, v134, v190
	v_fma_f32 v147, v147, v135, v191
	v_fma_f32 v148, v148, v136, v192
	v_fma_f32 v149, v149, v137, v193
	v_cvt_pk_bf16_f32 v152, v146, v147
	v_cvt_pk_bf16_f32 v153, v148, v149
	global_store_dwordx2 v157, v[152:153], s[44:45] offset:32
	v_mul_f32_e32 v146, v165, v38
	v_mul_f32_e32 v147, v165, v39
	v_mul_f32_e32 v148, v165, v40
	v_mul_f32_e32 v149, v165, v41
	v_fma_f32 v146, v146, v138, v194
	v_fma_f32 v147, v147, v139, v195
	v_fma_f32 v148, v148, v140, v196
	v_fma_f32 v149, v149, v141, v197
	v_cvt_pk_bf16_f32 v154, v146, v147
	v_cvt_pk_bf16_f32 v155, v148, v149
	global_store_dwordx2 v157, v[154:155], s[44:45] offset:256
	v_mul_f32_e32 v146, v165, v34
	v_mul_f32_e32 v147, v165, v35
	v_mul_f32_e32 v148, v165, v36
	v_mul_f32_e32 v149, v165, v37
	v_fma_f32 v146, v146, v142, v198
	v_fma_f32 v147, v147, v143, v199
	v_fma_f32 v148, v148, v144, v200
	v_fma_f32 v149, v149, v145, v201
	v_cvt_pk_bf16_f32 v158, v146, v147
	v_cvt_pk_bf16_f32 v159, v148, v149
	global_store_dwordx2 v157, v[158:159], s[44:45] offset:288
	s_add_u32 s44, s44, 0x28000
	s_addc_u32 s45, s45, 0
	v_mul_f32_e32 v146, v166, v94
	v_mul_f32_e32 v147, v166, v95
	v_mul_f32_e32 v148, v166, v96
	v_mul_f32_e32 v149, v166, v97
	v_fma_f32 v146, v146, v130, v186
	v_fma_f32 v147, v147, v131, v187
	v_fma_f32 v148, v148, v132, v188
	v_fma_f32 v149, v149, v133, v189
	v_cvt_pk_bf16_f32 v150, v146, v147
	v_cvt_pk_bf16_f32 v151, v148, v149
	global_store_dwordx2 v157, v[150:151], s[44:45]
	v_mul_f32_e32 v146, v166, v90
	v_mul_f32_e32 v147, v166, v91
	v_mul_f32_e32 v148, v166, v92
	v_mul_f32_e32 v149, v166, v93
	v_fma_f32 v146, v146, v134, v190
	v_fma_f32 v147, v147, v135, v191
	v_fma_f32 v148, v148, v136, v192
	v_fma_f32 v149, v149, v137, v193
	v_cvt_pk_bf16_f32 v152, v146, v147
	v_cvt_pk_bf16_f32 v153, v148, v149
	global_store_dwordx2 v157, v[152:153], s[44:45] offset:32
	v_mul_f32_e32 v146, v166, v30
	v_mul_f32_e32 v147, v166, v31
	v_mul_f32_e32 v148, v166, v32
	v_mul_f32_e32 v149, v166, v33
	v_fma_f32 v146, v146, v138, v194
	v_fma_f32 v147, v147, v139, v195
	v_fma_f32 v148, v148, v140, v196
	v_fma_f32 v149, v149, v141, v197
	v_cvt_pk_bf16_f32 v154, v146, v147
	v_cvt_pk_bf16_f32 v155, v148, v149
	global_store_dwordx2 v157, v[154:155], s[44:45] offset:256
	v_mul_f32_e32 v146, v166, v26
	v_mul_f32_e32 v147, v166, v27
	v_mul_f32_e32 v148, v166, v28
	v_mul_f32_e32 v149, v166, v29
	v_fma_f32 v146, v146, v142, v198
	v_fma_f32 v147, v147, v143, v199
	v_fma_f32 v148, v148, v144, v200
	v_fma_f32 v149, v149, v145, v201
	v_cvt_pk_bf16_f32 v158, v146, v147
	v_cvt_pk_bf16_f32 v159, v148, v149
	global_store_dwordx2 v157, v[158:159], s[44:45] offset:288
	s_add_u32 s44, s44, 0x8000
	s_addc_u32 s45, s45, 0
	v_mul_f32_e32 v146, v167, v86
	v_mul_f32_e32 v147, v167, v87
	v_mul_f32_e32 v148, v167, v88
	v_mul_f32_e32 v149, v167, v89
	v_fma_f32 v146, v146, v130, v186
	v_fma_f32 v147, v147, v131, v187
	v_fma_f32 v148, v148, v132, v188
	v_fma_f32 v149, v149, v133, v189
	v_cvt_pk_bf16_f32 v150, v146, v147
	v_cvt_pk_bf16_f32 v151, v148, v149
	global_store_dwordx2 v157, v[150:151], s[44:45]
	v_mul_f32_e32 v146, v167, v82
	v_mul_f32_e32 v147, v167, v83
	v_mul_f32_e32 v148, v167, v84
	v_mul_f32_e32 v149, v167, v85
	v_fma_f32 v146, v146, v134, v190
	v_fma_f32 v147, v147, v135, v191
	v_fma_f32 v148, v148, v136, v192
	v_fma_f32 v149, v149, v137, v193
	v_cvt_pk_bf16_f32 v152, v146, v147
	v_cvt_pk_bf16_f32 v153, v148, v149
	global_store_dwordx2 v157, v[152:153], s[44:45] offset:32
	v_mul_f32_e32 v146, v167, v22
	v_mul_f32_e32 v147, v167, v23
	v_mul_f32_e32 v148, v167, v24
	v_mul_f32_e32 v149, v167, v25
	v_fma_f32 v146, v146, v138, v194
	v_fma_f32 v147, v147, v139, v195
	v_fma_f32 v148, v148, v140, v196
	v_fma_f32 v149, v149, v141, v197
	v_cvt_pk_bf16_f32 v154, v146, v147
	v_cvt_pk_bf16_f32 v155, v148, v149
	global_store_dwordx2 v157, v[154:155], s[44:45] offset:256
	v_mul_f32_e32 v146, v167, v18
	v_mul_f32_e32 v147, v167, v19
	v_mul_f32_e32 v148, v167, v20
	v_mul_f32_e32 v149, v167, v21
	v_fma_f32 v146, v146, v142, v198
	v_fma_f32 v147, v147, v143, v199
	v_fma_f32 v148, v148, v144, v200
	v_fma_f32 v149, v149, v145, v201
	v_cvt_pk_bf16_f32 v158, v146, v147
	v_cvt_pk_bf16_f32 v159, v148, v149
	global_store_dwordx2 v157, v[158:159], s[44:45] offset:288
	s_add_u32 s44, s44, 0x8000
	s_addc_u32 s45, s45, 0
	v_mul_f32_e32 v146, v168, v78
	v_mul_f32_e32 v147, v168, v79
	v_mul_f32_e32 v148, v168, v80
	v_mul_f32_e32 v149, v168, v81
	v_fma_f32 v146, v146, v130, v186
	v_fma_f32 v147, v147, v131, v187
	v_fma_f32 v148, v148, v132, v188
	v_fma_f32 v149, v149, v133, v189
	v_cvt_pk_bf16_f32 v150, v146, v147
	v_cvt_pk_bf16_f32 v151, v148, v149
	global_store_dwordx2 v157, v[150:151], s[44:45]
	v_mul_f32_e32 v146, v168, v74
	v_mul_f32_e32 v147, v168, v75
	v_mul_f32_e32 v148, v168, v76
	v_mul_f32_e32 v149, v168, v77
	v_fma_f32 v146, v146, v134, v190
	v_fma_f32 v147, v147, v135, v191
	v_fma_f32 v148, v148, v136, v192
	v_fma_f32 v149, v149, v137, v193
	v_cvt_pk_bf16_f32 v152, v146, v147
	v_cvt_pk_bf16_f32 v153, v148, v149
	global_store_dwordx2 v157, v[152:153], s[44:45] offset:32
	v_mul_f32_e32 v146, v168, v14
	v_mul_f32_e32 v147, v168, v15
	v_mul_f32_e32 v148, v168, v16
	v_mul_f32_e32 v149, v168, v17
	v_fma_f32 v146, v146, v138, v194
	v_fma_f32 v147, v147, v139, v195
	v_fma_f32 v148, v148, v140, v196
	v_fma_f32 v149, v149, v141, v197
	v_cvt_pk_bf16_f32 v154, v146, v147
	v_cvt_pk_bf16_f32 v155, v148, v149
	global_store_dwordx2 v157, v[154:155], s[44:45] offset:256
	v_mul_f32_e32 v146, v168, v10
	v_mul_f32_e32 v147, v168, v11
	v_mul_f32_e32 v148, v168, v12
	v_mul_f32_e32 v149, v168, v13
	v_fma_f32 v146, v146, v142, v198
	v_fma_f32 v147, v147, v143, v199
	v_fma_f32 v148, v148, v144, v200
	v_fma_f32 v149, v149, v145, v201
	v_cvt_pk_bf16_f32 v158, v146, v147
	v_cvt_pk_bf16_f32 v159, v148, v149
	global_store_dwordx2 v157, v[158:159], s[44:45] offset:288
	s_add_u32 s44, s44, 0x8000
	s_addc_u32 s45, s45, 0
	v_mul_f32_e32 v146, v169, v70
	v_mul_f32_e32 v147, v169, v71
	v_mul_f32_e32 v148, v169, v72
	v_mul_f32_e32 v149, v169, v73
	v_fma_f32 v146, v146, v130, v186
	v_fma_f32 v147, v147, v131, v187
	v_fma_f32 v148, v148, v132, v188
	v_fma_f32 v149, v149, v133, v189
	v_cvt_pk_bf16_f32 v150, v146, v147
	v_cvt_pk_bf16_f32 v151, v148, v149
	global_store_dwordx2 v157, v[150:151], s[44:45]
	v_mul_f32_e32 v146, v169, v66
	v_mul_f32_e32 v147, v169, v67
	v_mul_f32_e32 v148, v169, v68
	v_mul_f32_e32 v149, v169, v69
	v_fma_f32 v146, v146, v134, v190
	v_fma_f32 v147, v147, v135, v191
	v_fma_f32 v148, v148, v136, v192
	v_fma_f32 v149, v149, v137, v193
	v_cvt_pk_bf16_f32 v152, v146, v147
	v_cvt_pk_bf16_f32 v153, v148, v149
	global_store_dwordx2 v157, v[152:153], s[44:45] offset:32
	v_mul_f32_e32 v146, v169, v6
	v_mul_f32_e32 v147, v169, v7
	v_mul_f32_e32 v148, v169, v8
	v_mul_f32_e32 v149, v169, v9
	v_fma_f32 v146, v146, v138, v194
	v_fma_f32 v147, v147, v139, v195
	v_fma_f32 v148, v148, v140, v196
	v_fma_f32 v149, v149, v141, v197
	v_cvt_pk_bf16_f32 v154, v146, v147
	v_cvt_pk_bf16_f32 v155, v148, v149
	global_store_dwordx2 v157, v[154:155], s[44:45] offset:256
	v_mul_f32_e32 v146, v169, v2
	v_mul_f32_e32 v147, v169, v3
	v_mul_f32_e32 v148, v169, v4
	v_mul_f32_e32 v149, v169, v5
	v_fma_f32 v146, v146, v142, v198
	v_fma_f32 v147, v147, v143, v199
	v_fma_f32 v148, v148, v144, v200
	v_fma_f32 v149, v149, v145, v201
	v_cvt_pk_bf16_f32 v158, v146, v147
	v_cvt_pk_bf16_f32 v159, v148, v149
	global_store_dwordx2 v157, v[158:159], s[44:45] offset:288
	s_branch .Lfz_odone
.Lfz_ofin:
	v_readlane_b32 s2, v252, 5
	v_readlane_b32 s3, v252, 6
	s_sub_u32 s44, s88, s2
	s_subb_u32 s45, s89, s3
	s_add_u32 s44, s44, s6
	s_addc_u32 s45, s45, s7
	v_mul_f32_e32 v146, v162, v126
	v_mul_f32_e32 v147, v162, v127
	v_mul_f32_e32 v148, v162, v128
	v_mul_f32_e32 v149, v162, v129
	v_mul_f32_e32 v146, v146, v130
	v_mul_f32_e32 v147, v147, v131
	v_mul_f32_e32 v148, v148, v132
	v_mul_f32_e32 v149, v149, v133
	global_store_dwordx4 v178, v[146:149], s[44:45]
	v_mul_f32_e32 v150, v162, v122
	v_mul_f32_e32 v151, v162, v123
	v_mul_f32_e32 v152, v162, v124
	v_mul_f32_e32 v153, v162, v125
	v_mul_f32_e32 v150, v150, v134
	v_mul_f32_e32 v151, v151, v135
	v_mul_f32_e32 v152, v152, v136
	v_mul_f32_e32 v153, v153, v137
	global_store_dwordx4 v178, v[150:153], s[44:45] offset:64
	v_mul_f32_e32 v154, v162, v62
	v_mul_f32_e32 v155, v162, v63
	v_mul_f32_e32 v156, v162, v64
	v_mul_f32_e32 v157, v162, v65
	v_mul_f32_e32 v154, v154, v138
	v_mul_f32_e32 v155, v155, v139
	v_mul_f32_e32 v156, v156, v140
	v_mul_f32_e32 v157, v157, v141
	global_store_dwordx4 v178, v[154:157], s[44:45] offset:512
	v_mul_f32_e32 v146, v162, v58
	v_mul_f32_e32 v147, v162, v59
	v_mul_f32_e32 v148, v162, v60
	v_mul_f32_e32 v149, v162, v61
	v_mul_f32_e32 v146, v146, v142
	v_mul_f32_e32 v147, v147, v143
	v_mul_f32_e32 v148, v148, v144
	v_mul_f32_e32 v149, v149, v145
	global_store_dwordx4 v178, v[146:149], s[44:45] offset:576
	s_add_u32 s44, s44, 0x10000
	s_addc_u32 s45, s45, 0
	v_mul_f32_e32 v150, v163, v118
	v_mul_f32_e32 v151, v163, v119
	v_mul_f32_e32 v152, v163, v120
	v_mul_f32_e32 v153, v163, v121
	v_mul_f32_e32 v150, v150, v130
	v_mul_f32_e32 v151, v151, v131
	v_mul_f32_e32 v152, v152, v132
	v_mul_f32_e32 v153, v153, v133
	global_store_dwordx4 v178, v[150:153], s[44:45]
	v_mul_f32_e32 v154, v163, v114
	v_mul_f32_e32 v155, v163, v115
	v_mul_f32_e32 v156, v163, v116
	v_mul_f32_e32 v157, v163, v117
	v_mul_f32_e32 v154, v154, v134
	v_mul_f32_e32 v155, v155, v135
	v_mul_f32_e32 v156, v156, v136
	v_mul_f32_e32 v157, v157, v137
	global_store_dwordx4 v178, v[154:157], s[44:45] offset:64
	v_mul_f32_e32 v146, v163, v54
	v_mul_f32_e32 v147, v163, v55
	v_mul_f32_e32 v148, v163, v56
	v_mul_f32_e32 v149, v163, v57
	v_mul_f32_e32 v146, v146, v138
	v_mul_f32_e32 v147, v147, v139
	v_mul_f32_e32 v148, v148, v140
	v_mul_f32_e32 v149, v149, v141
	global_store_dwordx4 v178, v[146:149], s[44:45] offset:512
	v_mul_f32_e32 v150, v163, v50
	v_mul_f32_e32 v151, v163, v51
	v_mul_f32_e32 v152, v163, v52
	v_mul_f32_e32 v153, v163, v53
	v_mul_f32_e32 v150, v150, v142
	v_mul_f32_e32 v151, v151, v143
	v_mul_f32_e32 v152, v152, v144
	v_mul_f32_e32 v153, v153, v145
	global_store_dwordx4 v178, v[150:153], s[44:45] offset:576
	s_add_u32 s44, s44, 0x10000
	s_addc_u32 s45, s45, 0
	v_mul_f32_e32 v154, v164, v110
	v_mul_f32_e32 v155, v164, v111
	v_mul_f32_e32 v156, v164, v112
	v_mul_f32_e32 v157, v164, v113
	v_mul_f32_e32 v154, v154, v130
	v_mul_f32_e32 v155, v155, v131
	v_mul_f32_e32 v156, v156, v132
	v_mul_f32_e32 v157, v157, v133
	global_store_dwordx4 v178, v[154:157], s[44:45]
	v_mul_f32_e32 v146, v164, v106
	v_mul_f32_e32 v147, v164, v107
	v_mul_f32_e32 v148, v164, v108
	v_mul_f32_e32 v149, v164, v109
	v_mul_f32_e32 v146, v146, v134
	v_mul_f32_e32 v147, v147, v135
	v_mul_f32_e32 v148, v148, v136
	v_mul_f32_e32 v149, v149, v137
	global_store_dwordx4 v178, v[146:149], s[44:45] offset:64
	v_mul_f32_e32 v150, v164, v46
	v_mul_f32_e32 v151, v164, v47
	v_mul_f32_e32 v152, v164, v48
	v_mul_f32_e32 v153, v164, v49
	v_mul_f32_e32 v150, v150, v138
	v_mul_f32_e32 v151, v151, v139
	v_mul_f32_e32 v152, v152, v140
	v_mul_f32_e32 v153, v153, v141
	global_store_dwordx4 v178, v[150:153], s[44:45] offset:512
	v_mul_f32_e32 v154, v164, v42
	v_mul_f32_e32 v155, v164, v43
	v_mul_f32_e32 v156, v164, v44
	v_mul_f32_e32 v157, v164, v45
	v_mul_f32_e32 v154, v154, v142
	v_mul_f32_e32 v155, v155, v143
	v_mul_f32_e32 v156, v156, v144
	v_mul_f32_e32 v157, v157, v145
	global_store_dwordx4 v178, v[154:157], s[44:45] offset:576
	s_add_u32 s44, s44, 0x10000
	s_addc_u32 s45, s45, 0
	v_mul_f32_e32 v146, v165, v102
	v_mul_f32_e32 v147, v165, v103
	v_mul_f32_e32 v148, v165, v104
	v_mul_f32_e32 v149, v165, v105
	v_mul_f32_e32 v146, v146, v130
	v_mul_f32_e32 v147, v147, v131
	v_mul_f32_e32 v148, v148, v132
	v_mul_f32_e32 v149, v149, v133
	global_store_dwordx4 v178, v[146:149], s[44:45]
	v_mul_f32_e32 v150, v165, v98
	v_mul_f32_e32 v151, v165, v99
	v_mul_f32_e32 v152, v165, v100
	v_mul_f32_e32 v153, v165, v101
	v_mul_f32_e32 v150, v150, v134
	v_mul_f32_e32 v151, v151, v135
	v_mul_f32_e32 v152, v152, v136
	v_mul_f32_e32 v153, v153, v137
	global_store_dwordx4 v178, v[150:153], s[44:45] offset:64
	v_mul_f32_e32 v154, v165, v38
	v_mul_f32_e32 v155, v165, v39
	v_mul_f32_e32 v156, v165, v40
	v_mul_f32_e32 v157, v165, v41
	v_mul_f32_e32 v154, v154, v138
	v_mul_f32_e32 v155, v155, v139
	v_mul_f32_e32 v156, v156, v140
	v_mul_f32_e32 v157, v157, v141
	global_store_dwordx4 v178, v[154:157], s[44:45] offset:512
	v_mul_f32_e32 v146, v165, v34
	v_mul_f32_e32 v147, v165, v35
	v_mul_f32_e32 v148, v165, v36
	v_mul_f32_e32 v149, v165, v37
	v_mul_f32_e32 v146, v146, v142
	v_mul_f32_e32 v147, v147, v143
	v_mul_f32_e32 v148, v148, v144
	v_mul_f32_e32 v149, v149, v145
	global_store_dwordx4 v178, v[146:149], s[44:45] offset:576
	s_add_u32 s44, s44, 0x50000
	s_addc_u32 s45, s45, 0
	v_mul_f32_e32 v150, v166, v94
	v_mul_f32_e32 v151, v166, v95
	v_mul_f32_e32 v152, v166, v96
	v_mul_f32_e32 v153, v166, v97
	v_mul_f32_e32 v150, v150, v130
	v_mul_f32_e32 v151, v151, v131
	v_mul_f32_e32 v152, v152, v132
	v_mul_f32_e32 v153, v153, v133
	global_store_dwordx4 v178, v[150:153], s[44:45]
	v_mul_f32_e32 v154, v166, v90
	v_mul_f32_e32 v155, v166, v91
	v_mul_f32_e32 v156, v166, v92
	v_mul_f32_e32 v157, v166, v93
	v_mul_f32_e32 v154, v154, v134
	v_mul_f32_e32 v155, v155, v135
	v_mul_f32_e32 v156, v156, v136
	v_mul_f32_e32 v157, v157, v137
	global_store_dwordx4 v178, v[154:157], s[44:45] offset:64
	v_mul_f32_e32 v146, v166, v30
	v_mul_f32_e32 v147, v166, v31
	v_mul_f32_e32 v148, v166, v32
	v_mul_f32_e32 v149, v166, v33
	v_mul_f32_e32 v146, v146, v138
	v_mul_f32_e32 v147, v147, v139
	v_mul_f32_e32 v148, v148, v140
	v_mul_f32_e32 v149, v149, v141
	global_store_dwordx4 v178, v[146:149], s[44:45] offset:512
	v_mul_f32_e32 v150, v166, v26
	v_mul_f32_e32 v151, v166, v27
	v_mul_f32_e32 v152, v166, v28
	v_mul_f32_e32 v153, v166, v29
	v_mul_f32_e32 v150, v150, v142
	v_mul_f32_e32 v151, v151, v143
	v_mul_f32_e32 v152, v152, v144
	v_mul_f32_e32 v153, v153, v145
	global_store_dwordx4 v178, v[150:153], s[44:45] offset:576
	s_add_u32 s44, s44, 0x10000
	s_addc_u32 s45, s45, 0
	v_mul_f32_e32 v154, v167, v86
	v_mul_f32_e32 v155, v167, v87
	v_mul_f32_e32 v156, v167, v88
	v_mul_f32_e32 v157, v167, v89
	v_mul_f32_e32 v154, v154, v130
	v_mul_f32_e32 v155, v155, v131
	v_mul_f32_e32 v156, v156, v132
	v_mul_f32_e32 v157, v157, v133
	global_store_dwordx4 v178, v[154:157], s[44:45]
	v_mul_f32_e32 v146, v167, v82
	v_mul_f32_e32 v147, v167, v83
	v_mul_f32_e32 v148, v167, v84
	v_mul_f32_e32 v149, v167, v85
	v_mul_f32_e32 v146, v146, v134
	v_mul_f32_e32 v147, v147, v135
	v_mul_f32_e32 v148, v148, v136
	v_mul_f32_e32 v149, v149, v137
	global_store_dwordx4 v178, v[146:149], s[44:45] offset:64
	v_mul_f32_e32 v150, v167, v22
	v_mul_f32_e32 v151, v167, v23
	v_mul_f32_e32 v152, v167, v24
	v_mul_f32_e32 v153, v167, v25
	v_mul_f32_e32 v150, v150, v138
	v_mul_f32_e32 v151, v151, v139
	v_mul_f32_e32 v152, v152, v140
	v_mul_f32_e32 v153, v153, v141
	global_store_dwordx4 v178, v[150:153], s[44:45] offset:512
	v_mul_f32_e32 v154, v167, v18
	v_mul_f32_e32 v155, v167, v19
	v_mul_f32_e32 v156, v167, v20
	v_mul_f32_e32 v157, v167, v21
	v_mul_f32_e32 v154, v154, v142
	v_mul_f32_e32 v155, v155, v143
	v_mul_f32_e32 v156, v156, v144
	v_mul_f32_e32 v157, v157, v145
	global_store_dwordx4 v178, v[154:157], s[44:45] offset:576
	s_add_u32 s44, s44, 0x10000
	s_addc_u32 s45, s45, 0
	v_mul_f32_e32 v146, v168, v78
	v_mul_f32_e32 v147, v168, v79
	v_mul_f32_e32 v148, v168, v80
	v_mul_f32_e32 v149, v168, v81
	v_mul_f32_e32 v146, v146, v130
	v_mul_f32_e32 v147, v147, v131
	v_mul_f32_e32 v148, v148, v132
	v_mul_f32_e32 v149, v149, v133
	global_store_dwordx4 v178, v[146:149], s[44:45]
	v_mul_f32_e32 v150, v168, v74
	v_mul_f32_e32 v151, v168, v75
	v_mul_f32_e32 v152, v168, v76
	v_mul_f32_e32 v153, v168, v77
	v_mul_f32_e32 v150, v150, v134
	v_mul_f32_e32 v151, v151, v135
	v_mul_f32_e32 v152, v152, v136
	v_mul_f32_e32 v153, v153, v137
	global_store_dwordx4 v178, v[150:153], s[44:45] offset:64
	v_mul_f32_e32 v154, v168, v14
	v_mul_f32_e32 v155, v168, v15
	v_mul_f32_e32 v156, v168, v16
	v_mul_f32_e32 v157, v168, v17
	v_mul_f32_e32 v154, v154, v138
	v_mul_f32_e32 v155, v155, v139
	v_mul_f32_e32 v156, v156, v140
	v_mul_f32_e32 v157, v157, v141
	global_store_dwordx4 v178, v[154:157], s[44:45] offset:512
	v_mul_f32_e32 v146, v168, v10
	v_mul_f32_e32 v147, v168, v11
	v_mul_f32_e32 v148, v168, v12
	v_mul_f32_e32 v149, v168, v13
	v_mul_f32_e32 v146, v146, v142
	v_mul_f32_e32 v147, v147, v143
	v_mul_f32_e32 v148, v148, v144
	v_mul_f32_e32 v149, v149, v145
	global_store_dwordx4 v178, v[146:149], s[44:45] offset:576
	s_add_u32 s44, s44, 0x10000
	s_addc_u32 s45, s45, 0
	v_mul_f32_e32 v150, v169, v70
	v_mul_f32_e32 v151, v169, v71
	v_mul_f32_e32 v152, v169, v72
	v_mul_f32_e32 v153, v169, v73
	v_mul_f32_e32 v150, v150, v130
	v_mul_f32_e32 v151, v151, v131
	v_mul_f32_e32 v152, v152, v132
	v_mul_f32_e32 v153, v153, v133
	global_store_dwordx4 v178, v[150:153], s[44:45]
	v_mul_f32_e32 v154, v169, v66
	v_mul_f32_e32 v155, v169, v67
	v_mul_f32_e32 v156, v169, v68
	v_mul_f32_e32 v157, v169, v69
	v_mul_f32_e32 v154, v154, v134
	v_mul_f32_e32 v155, v155, v135
	v_mul_f32_e32 v156, v156, v136
	v_mul_f32_e32 v157, v157, v137
	global_store_dwordx4 v178, v[154:157], s[44:45] offset:64
	v_mul_f32_e32 v146, v169, v6
	v_mul_f32_e32 v147, v169, v7
	v_mul_f32_e32 v148, v169, v8
	v_mul_f32_e32 v149, v169, v9
	v_mul_f32_e32 v146, v146, v138
	v_mul_f32_e32 v147, v147, v139
	v_mul_f32_e32 v148, v148, v140
	v_mul_f32_e32 v149, v149, v141
	global_store_dwordx4 v178, v[146:149], s[44:45] offset:512
	v_mul_f32_e32 v150, v169, v2
	v_mul_f32_e32 v151, v169, v3
	v_mul_f32_e32 v152, v169, v4
	v_mul_f32_e32 v153, v169, v5
	v_mul_f32_e32 v150, v150, v142
	v_mul_f32_e32 v151, v151, v143
	v_mul_f32_e32 v152, v152, v144
	v_mul_f32_e32 v153, v153, v145
	global_store_dwordx4 v178, v[150:153], s[44:45] offset:576
.Lfz_odone:
	s_cmpk_gt_u32 s49, 0xff
	s_cbranch_scc0 .Lfz_skip
	s_barrier

.LBB0_549:
.LBB0_550:
	s_add_i32 s10, s10, 1
	v_readlane_b32 s0, v252, 2
	s_cmp_eq_u32 s0, 0x100
	s_cselect_b32 s0, 37, -1
	s_cmp_eq_u32 s10, s0
	s_cselect_b32 s10, 38, s10
	s_cmp_ge_i32 s10, s11
	s_mov_b64 s[0:1], -1
	s_cbranch_scc0 .LBB0_551
	s_getpc_b64 s[98:99]
